# v47 + grid barrier: XCD leaders add TOP without return and poll TOP until (gen+1)*nx (no TOPGEN hop, no divide on the release chain)
# speedup vs baseline: 1.0020x; 1.0001x over previous
; __device__ __forceinline__ unsigned xb_ld(unsigned* p)              { return __hip_atomic_load(p, __ATOMIC_RELAXED, __HIP_MEMORY_SCOPE_AGENT); }
; __device__ __forceinline__ unsigned xb_add(unsigned* p, unsigned v) { return __hip_atomic_fetch_add(p, v, __ATOMIC_RELAXED, __HIP_MEMORY_SCOPE_AGENT); }
; #define XB_SPIN(cond, bar) do { unsigned _sp = 0; while (cond) { __builtin_amdgcn_s_sleep(1); \
;     if ((++_sp & 255u) == 0u) { if (xb_ld(&(bar)[XB_TMO])) break; if (_sp > XB_SPIN_CAP) { atomicAdd(&(bar)[XB_TMO], 1u); break; } } } } while (0)
; __device__ __forceinline__ void xcd_barrier(const XcdBarrier& b) {
;     ...
;         const unsigned old = xb_add(&bar[XB_XSUB(b.x)], 1u);
;         const unsigned gen = old / nloc;
;         if (old + 1u == (gen + 1u) * nloc) {
;             __builtin_amdgcn_fence(__ATOMIC_RELEASE, "agent");
;             asm volatile("s_waitcnt vmcnt(0)" ::: "memory");
;             const unsigned og = xb_add(&bar[XB_TOP], 1u);
;             const unsigned tg = og / nx;
;             if (og + 1u == (tg + 1u) * nx) xb_add(&bar[XB_TOPGEN], 1u);
;             else XB_SPIN(xb_ld(&bar[XB_TOPGEN]) == tg, bar);
;             __builtin_amdgcn_fence(__ATOMIC_ACQUIRE, "agent");
;             xb_add(&bar[XB_XGEN(b.x)], 1u);
;             asm volatile("s_waitcnt vmcnt(0)" ::: "memory");
;         } else {
;             XB_SPIN(xb_ld(&bar[XB_XGEN(b.x)]) == gen, bar);
;             __builtin_amdgcn_fence(__ATOMIC_ACQUIRE, "agent");
;             asm volatile("s_waitcnt vmcnt(0)" ::: "memory");
.LBB0_154:
	s_andn2_saveexec_b64 s[6:7], s[6:7]
	s_cbranch_execz .LBB0_174
	s_mov_b64 s[6:7], exec
	buffer_wbl2 sc1
	s_waitcnt lgkmcnt(0)
	s_waitcnt vmcnt(0)
	v_mov_b32_e32 v2, 0x23000
	v_mov_b32_e32 v3, 1
	global_atomic_add v2, v3, s[30:31] offset:1024
	v_add_u32_e32 v4, 1, v1
	v_mul_lo_u32 v4, v4, v0
	s_mov_b32 s100, 0
.Ltop_spin_7:
	global_load_dword v5, v2, s[30:31] offset:1024 sc1
	s_waitcnt vmcnt(0)
	v_cmp_ge_u32_e32 vcc, v5, v4
	s_cbranch_vccnz .Ltop_done_7
	s_sleep 1
	s_add_i32 s100, s100, 1
	s_cmp_lt_u32 s100, 0x40000
	s_cbranch_scc1 .Ltop_spin_7
.Ltop_done_7:
	s_mov_b64 s[6:7], exec
.LBB0_171:
	s_or_b64 exec, exec, s[6:7]
	s_mov_b64 s[6:7], exec
	v_mbcnt_lo_u32_b32 v0, s6, 0
	v_mbcnt_hi_u32_b32 v0, s7, v0
	v_cmp_eq_u32_e32 vcc, 0, v0
	s_waitcnt vmcnt(0)
	buffer_inv sc1
	s_and_saveexec_b64 s[8:9], vcc
	s_cbranch_execz .LBB0_173
	s_bcnt1_i32_b64 s6, s[6:7]
	v_mov_b32_e32 v0, 0x2000
	v_mov_b32_e32 v1, s6
	global_atomic_add v0, v1, s[4:5] offset:1024

; __device__ __forceinline__ unsigned xb_ld(unsigned* p)              { return __hip_atomic_load(p, __ATOMIC_RELAXED, __HIP_MEMORY_SCOPE_AGENT); }
; __device__ __forceinline__ unsigned xb_add(unsigned* p, unsigned v) { return __hip_atomic_fetch_add(p, v, __ATOMIC_RELAXED, __HIP_MEMORY_SCOPE_AGENT); }
; #define XB_SPIN(cond, bar) do { unsigned _sp = 0; while (cond) { __builtin_amdgcn_s_sleep(1); \
;     if ((++_sp & 255u) == 0u) { if (xb_ld(&(bar)[XB_TMO])) break; if (_sp > XB_SPIN_CAP) { atomicAdd(&(bar)[XB_TMO], 1u); break; } } } } while (0)
; __device__ __forceinline__ void xcd_barrier(const XcdBarrier& b) {
;     ...
;         if (old + 1u == (gen + 1u) * nloc) {
;             __builtin_amdgcn_fence(__ATOMIC_RELEASE, "agent");
;             asm volatile("s_waitcnt vmcnt(0)" ::: "memory");
;             const unsigned og = xb_add(&bar[XB_TOP], 1u);
;             const unsigned tg = og / nx;
;             if (og + 1u == (tg + 1u) * nx) xb_add(&bar[XB_TOPGEN], 1u);
;             else XB_SPIN(xb_ld(&bar[XB_TOPGEN]) == tg, bar);
;             __builtin_amdgcn_fence(__ATOMIC_ACQUIRE, "agent");
;             xb_add(&bar[XB_XGEN(b.x)], 1u);
.Ltop_done_6:
	s_mov_b64 s[6:7], exec
.LBB0_257:
	s_or_b64 exec, exec, s[6:7]
	s_mov_b64 s[6:7], exec
	v_mbcnt_lo_u32_b32 v0, s6, 0
	v_mbcnt_hi_u32_b32 v0, s7, v0
	v_cmp_eq_u32_e32 vcc, 0, v0
	s_waitcnt vmcnt(0)
	buffer_inv sc1
	s_and_saveexec_b64 s[8:9], vcc
	s_cbranch_execz .LBB0_259
	s_bcnt1_i32_b64 s6, s[6:7]
	v_mov_b32_e32 v0, 0x2000
	v_mov_b32_e32 v1, s6
	global_atomic_add v0, v1, s[4:5] offset:1024

; __device__ __forceinline__ unsigned xb_ld(unsigned* p)              { return __hip_atomic_load(p, __ATOMIC_RELAXED, __HIP_MEMORY_SCOPE_AGENT); }
; __device__ __forceinline__ unsigned xb_add(unsigned* p, unsigned v) { return __hip_atomic_fetch_add(p, v, __ATOMIC_RELAXED, __HIP_MEMORY_SCOPE_AGENT); }
; #define XB_SPIN(cond, bar) do { unsigned _sp = 0; while (cond) { __builtin_amdgcn_s_sleep(1); \
;     if ((++_sp & 255u) == 0u) { if (xb_ld(&(bar)[XB_TMO])) break; if (_sp > XB_SPIN_CAP) { atomicAdd(&(bar)[XB_TMO], 1u); break; } } } } while (0)
; __device__ __forceinline__ void xcd_barrier(const XcdBarrier& b) {
;     ...
;         if (old + 1u == (gen + 1u) * nloc) {
;             __builtin_amdgcn_fence(__ATOMIC_RELEASE, "agent");
;             asm volatile("s_waitcnt vmcnt(0)" ::: "memory");
;             const unsigned og = xb_add(&bar[XB_TOP], 1u);
;             const unsigned tg = og / nx;
;             if (og + 1u == (tg + 1u) * nx) xb_add(&bar[XB_TOPGEN], 1u);
;             else XB_SPIN(xb_ld(&bar[XB_TOPGEN]) == tg, bar);
;             __builtin_amdgcn_fence(__ATOMIC_ACQUIRE, "agent");
;             xb_add(&bar[XB_XGEN(b.x)], 1u);
.LBB0_411:
	s_andn2_saveexec_b64 s[8:9], s[8:9]
	s_cbranch_execz .LBB0_431
	s_mov_b64 s[8:9], exec
	buffer_wbl2 sc1
	s_waitcnt lgkmcnt(0)
	s_waitcnt vmcnt(0)
	v_mov_b32_e32 v2, 0x23000
	v_mov_b32_e32 v3, 1
	global_atomic_add v2, v3, s[30:31] offset:1024
	v_add_u32_e32 v4, 1, v1
	v_mul_lo_u32 v4, v4, v0
	s_mov_b32 s100, 0

; __device__ __forceinline__ unsigned xb_ld(unsigned* p)              { return __hip_atomic_load(p, __ATOMIC_RELAXED, __HIP_MEMORY_SCOPE_AGENT); }
; __device__ __forceinline__ unsigned xb_add(unsigned* p, unsigned v) { return __hip_atomic_fetch_add(p, v, __ATOMIC_RELAXED, __HIP_MEMORY_SCOPE_AGENT); }
; #define XB_SPIN(cond, bar) do { unsigned _sp = 0; while (cond) { __builtin_amdgcn_s_sleep(1); \
;     if ((++_sp & 255u) == 0u) { if (xb_ld(&(bar)[XB_TMO])) break; if (_sp > XB_SPIN_CAP) { atomicAdd(&(bar)[XB_TMO], 1u); break; } } } } while (0)
; __device__ __forceinline__ void xcd_barrier(const XcdBarrier& b) {
;     ...
;         if (old + 1u == (gen + 1u) * nloc) {
;             __builtin_amdgcn_fence(__ATOMIC_RELEASE, "agent");
;             asm volatile("s_waitcnt vmcnt(0)" ::: "memory");
;             const unsigned og = xb_add(&bar[XB_TOP], 1u);
;             const unsigned tg = og / nx;
;             if (og + 1u == (tg + 1u) * nx) xb_add(&bar[XB_TOPGEN], 1u);
;             else XB_SPIN(xb_ld(&bar[XB_TOPGEN]) == tg, bar);
;             __builtin_amdgcn_fence(__ATOMIC_ACQUIRE, "agent");
;             xb_add(&bar[XB_XGEN(b.x)], 1u);
.Ltop_done_5:
	s_mov_b64 s[8:9], exec
.LBB0_428:
	s_or_b64 exec, exec, s[8:9]
	s_mov_b64 s[8:9], exec
	v_mbcnt_lo_u32_b32 v0, s8, 0
	v_mbcnt_hi_u32_b32 v0, s9, v0
	v_cmp_eq_u32_e32 vcc, 0, v0
	s_waitcnt vmcnt(0)
	buffer_inv sc1
	s_and_saveexec_b64 s[22:23], vcc
	s_cbranch_execz .LBB0_430
	s_bcnt1_i32_b64 s8, s[8:9]
	v_mov_b32_e32 v0, 0x2000
	v_mov_b32_e32 v1, s8
	global_atomic_add v0, v1, s[4:5] offset:1024

; __device__ __forceinline__ unsigned xb_ld(unsigned* p)              { return __hip_atomic_load(p, __ATOMIC_RELAXED, __HIP_MEMORY_SCOPE_AGENT); }
; __device__ __forceinline__ unsigned xb_add(unsigned* p, unsigned v) { return __hip_atomic_fetch_add(p, v, __ATOMIC_RELAXED, __HIP_MEMORY_SCOPE_AGENT); }
; #define XB_SPIN(cond, bar) do { unsigned _sp = 0; while (cond) { __builtin_amdgcn_s_sleep(1); \
;     if ((++_sp & 255u) == 0u) { if (xb_ld(&(bar)[XB_TMO])) break; if (_sp > XB_SPIN_CAP) { atomicAdd(&(bar)[XB_TMO], 1u); break; } } } } while (0)
; __device__ __forceinline__ void xcd_barrier(const XcdBarrier& b) {
;     ...
;         if (old + 1u == (gen + 1u) * nloc) {
;             __builtin_amdgcn_fence(__ATOMIC_RELEASE, "agent");
;             asm volatile("s_waitcnt vmcnt(0)" ::: "memory");
;             const unsigned og = xb_add(&bar[XB_TOP], 1u);
;             const unsigned tg = og / nx;
;             if (og + 1u == (tg + 1u) * nx) xb_add(&bar[XB_TOPGEN], 1u);
;             else XB_SPIN(xb_ld(&bar[XB_TOPGEN]) == tg, bar);
;             __builtin_amdgcn_fence(__ATOMIC_ACQUIRE, "agent");
;             xb_add(&bar[XB_XGEN(b.x)], 1u);
.Ltop_done_4:
	s_mov_b64 s[8:9], exec
.LBB0_559:
	s_or_b64 exec, exec, s[8:9]
	s_mov_b64 s[8:9], exec
	v_mbcnt_lo_u32_b32 v0, s8, 0
	v_mbcnt_hi_u32_b32 v0, s9, v0
	v_cmp_eq_u32_e32 vcc, 0, v0
	s_waitcnt vmcnt(0)
	buffer_inv sc1
	s_and_saveexec_b64 s[22:23], vcc
	s_cbranch_execz .LBB0_561
	s_bcnt1_i32_b64 s8, s[8:9]
	v_mov_b32_e32 v0, 0x2000
	v_mov_b32_e32 v1, s8
	global_atomic_add v0, v1, s[4:5] offset:1024

; __device__ __forceinline__ unsigned xb_ld(unsigned* p)              { return __hip_atomic_load(p, __ATOMIC_RELAXED, __HIP_MEMORY_SCOPE_AGENT); }
; __device__ __forceinline__ unsigned xb_add(unsigned* p, unsigned v) { return __hip_atomic_fetch_add(p, v, __ATOMIC_RELAXED, __HIP_MEMORY_SCOPE_AGENT); }
; #define XB_SPIN(cond, bar) do { unsigned _sp = 0; while (cond) { __builtin_amdgcn_s_sleep(1); \
;     if ((++_sp & 255u) == 0u) { if (xb_ld(&(bar)[XB_TMO])) break; if (_sp > XB_SPIN_CAP) { atomicAdd(&(bar)[XB_TMO], 1u); break; } } } } while (0)
; __device__ __forceinline__ void xcd_barrier(const XcdBarrier& b) {
;     ...
;         if (old + 1u == (gen + 1u) * nloc) {
;             __builtin_amdgcn_fence(__ATOMIC_RELEASE, "agent");
;             asm volatile("s_waitcnt vmcnt(0)" ::: "memory");
;             const unsigned og = xb_add(&bar[XB_TOP], 1u);
;             const unsigned tg = og / nx;
;             if (og + 1u == (tg + 1u) * nx) xb_add(&bar[XB_TOPGEN], 1u);
;             else XB_SPIN(xb_ld(&bar[XB_TOPGEN]) == tg, bar);
;             __builtin_amdgcn_fence(__ATOMIC_ACQUIRE, "agent");
;             xb_add(&bar[XB_XGEN(b.x)], 1u);
.Ltop_done_3:
	s_mov_b64 s[8:9], exec
.LBB0_640:
	s_or_b64 exec, exec, s[8:9]
	s_mov_b64 s[8:9], exec
	v_mbcnt_lo_u32_b32 v0, s8, 0
	v_mbcnt_hi_u32_b32 v0, s9, v0
	v_cmp_eq_u32_e32 vcc, 0, v0
	s_waitcnt vmcnt(0)
	buffer_inv sc1
	s_and_saveexec_b64 s[22:23], vcc
	s_cbranch_execz .LBB0_642
	s_bcnt1_i32_b64 s8, s[8:9]
	v_mov_b32_e32 v0, 0x2000
	v_mov_b32_e32 v1, s8
	global_atomic_add v0, v1, s[4:5] offset:1024

; __device__ __forceinline__ unsigned xb_ld(unsigned* p)              { return __hip_atomic_load(p, __ATOMIC_RELAXED, __HIP_MEMORY_SCOPE_AGENT); }
; __device__ __forceinline__ unsigned xb_add(unsigned* p, unsigned v) { return __hip_atomic_fetch_add(p, v, __ATOMIC_RELAXED, __HIP_MEMORY_SCOPE_AGENT); }
; #define XB_SPIN(cond, bar) do { unsigned _sp = 0; while (cond) { __builtin_amdgcn_s_sleep(1); \
;     if ((++_sp & 255u) == 0u) { if (xb_ld(&(bar)[XB_TMO])) break; if (_sp > XB_SPIN_CAP) { atomicAdd(&(bar)[XB_TMO], 1u); break; } } } } while (0)
; __device__ __forceinline__ void xcd_barrier(const XcdBarrier& b) {
;     ...
;         if (old + 1u == (gen + 1u) * nloc) {
;             __builtin_amdgcn_fence(__ATOMIC_RELEASE, "agent");
;             asm volatile("s_waitcnt vmcnt(0)" ::: "memory");
;             const unsigned og = xb_add(&bar[XB_TOP], 1u);
;             const unsigned tg = og / nx;
;             if (og + 1u == (tg + 1u) * nx) xb_add(&bar[XB_TOPGEN], 1u);
;             else XB_SPIN(xb_ld(&bar[XB_TOPGEN]) == tg, bar);
;             __builtin_amdgcn_fence(__ATOMIC_ACQUIRE, "agent");
;             xb_add(&bar[XB_XGEN(b.x)], 1u);
.LBB0_730:
	s_andn2_saveexec_b64 s[4:5], s[4:5]
	s_cbranch_execz .LBB0_751
	s_mov_b64 s[4:5], exec
	buffer_wbl2 sc1
	s_waitcnt lgkmcnt(0)
	s_waitcnt vmcnt(0)
	v_mov_b32_e32 v2, 0x23000
	v_mov_b32_e32 v3, 1
	global_atomic_add v2, v3, s[30:31] offset:1024
	v_add_u32_e32 v4, 1, v1
	v_mul_lo_u32 v4, v4, v0
	s_mov_b32 s100, 0

; __device__ __forceinline__ unsigned xb_ld(unsigned* p)              { return __hip_atomic_load(p, __ATOMIC_RELAXED, __HIP_MEMORY_SCOPE_AGENT); }
; __device__ __forceinline__ unsigned xb_add(unsigned* p, unsigned v) { return __hip_atomic_fetch_add(p, v, __ATOMIC_RELAXED, __HIP_MEMORY_SCOPE_AGENT); }
; #define XB_SPIN(cond, bar) do { unsigned _sp = 0; while (cond) { __builtin_amdgcn_s_sleep(1); \
;     if ((++_sp & 255u) == 0u) { if (xb_ld(&(bar)[XB_TMO])) break; if (_sp > XB_SPIN_CAP) { atomicAdd(&(bar)[XB_TMO], 1u); break; } } } } while (0)
; __device__ __forceinline__ void xcd_barrier(const XcdBarrier& b) {
;     ...
;         if (old + 1u == (gen + 1u) * nloc) {
;             __builtin_amdgcn_fence(__ATOMIC_RELEASE, "agent");
;             asm volatile("s_waitcnt vmcnt(0)" ::: "memory");
;             const unsigned og = xb_add(&bar[XB_TOP], 1u);
;             const unsigned tg = og / nx;
;             if (og + 1u == (tg + 1u) * nx) xb_add(&bar[XB_TOPGEN], 1u);
;             else XB_SPIN(xb_ld(&bar[XB_TOPGEN]) == tg, bar);
;             __builtin_amdgcn_fence(__ATOMIC_ACQUIRE, "agent");
;             xb_add(&bar[XB_XGEN(b.x)], 1u);
.Ltop_done_2:
	s_mov_b64 s[4:5], exec
	s_branch .LBB0_748
.LBB0_743:
	s_branch .LBB0_668
.LBB0_748:
	s_or_b64 exec, exec, s[4:5]
	s_mov_b64 s[4:5], exec
	v_mbcnt_lo_u32_b32 v0, s4, 0
	v_mbcnt_hi_u32_b32 v0, s5, v0
	v_cmp_eq_u32_e32 vcc, 0, v0
	s_waitcnt vmcnt(0)
	buffer_inv sc1
	s_and_saveexec_b64 s[8:9], vcc
	s_cbranch_execz .LBB0_750
	s_bcnt1_i32_b64 s4, s[4:5]
	v_mov_b32_e32 v0, 0x2000
	v_mov_b32_e32 v1, s4
	global_atomic_add v0, v1, s[2:3] offset:1024

; __device__ __forceinline__ unsigned xb_ld(unsigned* p)              { return __hip_atomic_load(p, __ATOMIC_RELAXED, __HIP_MEMORY_SCOPE_AGENT); }
; __device__ __forceinline__ unsigned xb_add(unsigned* p, unsigned v) { return __hip_atomic_fetch_add(p, v, __ATOMIC_RELAXED, __HIP_MEMORY_SCOPE_AGENT); }
; #define XB_SPIN(cond, bar) do { unsigned _sp = 0; while (cond) { __builtin_amdgcn_s_sleep(1); \
;     if ((++_sp & 255u) == 0u) { if (xb_ld(&(bar)[XB_TMO])) break; if (_sp > XB_SPIN_CAP) { atomicAdd(&(bar)[XB_TMO], 1u); break; } } } } while (0)
; __device__ __forceinline__ void xcd_barrier(const XcdBarrier& b) {
;     ...
;         if (old + 1u == (gen + 1u) * nloc) {
;             __builtin_amdgcn_fence(__ATOMIC_RELEASE, "agent");
;             asm volatile("s_waitcnt vmcnt(0)" ::: "memory");
;             const unsigned og = xb_add(&bar[XB_TOP], 1u);
;             const unsigned tg = og / nx;
;             if (og + 1u == (tg + 1u) * nx) xb_add(&bar[XB_TOPGEN], 1u);
;             else XB_SPIN(xb_ld(&bar[XB_TOPGEN]) == tg, bar);
;             __builtin_amdgcn_fence(__ATOMIC_ACQUIRE, "agent");
;             xb_add(&bar[XB_XGEN(b.x)], 1u);
.Ltop_done_1:
	s_mov_b64 s[8:9], exec
.LBB0_812:
	s_or_b64 exec, exec, s[8:9]
	s_mov_b64 s[8:9], exec
	v_mbcnt_lo_u32_b32 v0, s8, 0
	v_mbcnt_hi_u32_b32 v0, s9, v0
	v_cmp_eq_u32_e32 vcc, 0, v0
	s_waitcnt vmcnt(0)
	buffer_inv sc1
	s_and_saveexec_b64 s[20:21], vcc
	s_cbranch_execz .LBB0_814
	s_bcnt1_i32_b64 s8, s[8:9]
	v_mov_b32_e32 v0, 0x2000
	v_mov_b32_e32 v1, s8
	global_atomic_add v0, v1, s[4:5] offset:1024

; __device__ __forceinline__ unsigned xb_ld(unsigned* p)              { return __hip_atomic_load(p, __ATOMIC_RELAXED, __HIP_MEMORY_SCOPE_AGENT); }
; __device__ __forceinline__ unsigned xb_add(unsigned* p, unsigned v) { return __hip_atomic_fetch_add(p, v, __ATOMIC_RELAXED, __HIP_MEMORY_SCOPE_AGENT); }
; #define XB_SPIN(cond, bar) do { unsigned _sp = 0; while (cond) { __builtin_amdgcn_s_sleep(1); \
;     if ((++_sp & 255u) == 0u) { if (xb_ld(&(bar)[XB_TMO])) break; if (_sp > XB_SPIN_CAP) { atomicAdd(&(bar)[XB_TMO], 1u); break; } } } } while (0)
; __device__ __forceinline__ void xcd_barrier(const XcdBarrier& b) {
;     ...
;         if (old + 1u == (gen + 1u) * nloc) {
;             __builtin_amdgcn_fence(__ATOMIC_RELEASE, "agent");
;             asm volatile("s_waitcnt vmcnt(0)" ::: "memory");
;             const unsigned og = xb_add(&bar[XB_TOP], 1u);
;             const unsigned tg = og / nx;
;             if (og + 1u == (tg + 1u) * nx) xb_add(&bar[XB_TOPGEN], 1u);
;             else XB_SPIN(xb_ld(&bar[XB_TOPGEN]) == tg, bar);
;             __builtin_amdgcn_fence(__ATOMIC_ACQUIRE, "agent");
;             xb_add(&bar[XB_XGEN(b.x)], 1u);
.Ltop_done_0:
	s_mov_b64 s[6:7], exec
.LBB0_891:
	s_or_b64 exec, exec, s[6:7]
	s_mov_b64 s[6:7], exec
	v_mbcnt_lo_u32_b32 v0, s6, 0
	v_mbcnt_hi_u32_b32 v0, s7, v0
	v_cmp_eq_u32_e32 vcc, 0, v0
	s_waitcnt vmcnt(0)
	buffer_inv sc1
	s_and_saveexec_b64 s[8:9], vcc
	s_cbranch_execz .LBB0_893
	s_bcnt1_i32_b64 s6, s[6:7]
	v_mov_b32_e32 v0, 0x2000
	v_mov_b32_e32 v1, s6
	global_atomic_add v0, v1, s[4:5] offset:1024
